# index PASS3/PASS2 main paths: raw partial sums swapped in place (the diagonal-tile alternative path is mutually exclusive), drops 4 copies per block
# baseline (speedup 1.0000x reference)
; DI float xhalf_sum(float v) { const auto r = __builtin_amdgcn_permlane32_swap(__float_as_uint(v), __float_as_uint(v), false, false); return __uint_as_float(r[0]) + __uint_as_float(r[1]); }
; DI void phase_index(const Params& p, unsigned char* lds) {
;     ...
;             for (int q = 0; q < 4; ++q) {
;                 float pr = 0.f;
; #pragma unroll
;                 for (int e = 0; e < 4; ++e) pr += wq[q][e] * fmaxf(s[4 * q + e], 0.f);
;                 tot[q] = xhalf_sum(pr);
;             }
;             const int key = k0 + 32 * kb + r32;
; #pragma unroll
;             for (int qq = 0; qq < 2; ++qq) {
;                 const float t_lo = tot[qq], t_hi = tot[2 + qq];
;                 const float sc = ((lane & 32) ? t_hi : t_lo) + 0.0f;
;                 const unsigned ub = __float_as_uint(sc);
;                 const unsigned uk = ub ^ ((unsigned)((int)ub >> 31) | 0x80000000u);
;                 const bool valid = DIAG ? (key <= tq0 + qq) : true;
;                 if (PASS == 0) {
;                     if (valid) { const unsigned a = (uk >> 21) & 0x7feu; atomicAdd((unsigned*)(lds + hbase0 + qq * 2048 + (a & ~3u)), 1u << ((a & 2u) << 3)); }
;                 } else if (PASS == 1) {
;                     if (valid && (int)(uk >> 22) == b1v[qq]) { const unsigned a = (uk >> 11) & 0x7feu; atomicAdd((unsigned*)(lds + hbase0 + qq * 2048 + (a & ~3u)), 1u << ((a & 2u) << 3)); }
;                 } else if (PASS == 3) {
;                     if (valid) {
;                         const int k10 = (int)(uk >> 22), d = k10 - b1v[qq];
;                         if (k10 > hiv[qq]) cntA[qq] += 1;
;                         else if (d >= 0) {
;                             const unsigned bin = ((unsigned)d << sbv[qq]) | ((uk >> (22 - sbv[qq])) & ((1u << sbv[qq]) - 1u));
;                             const unsigned a = bin << 1;
;                             atomicAdd((unsigned*)(lds + hbase0 + qq * 2048 + (a & ~3u)), 1u << ((a & 2u) << 3));
;                         }
;                     }
.LBB0_2639:
	v_max_f32_e32 v18, 0, v18
	v_fma_f32 v168, v50, v18, 0
	v_max_f32_e32 v18, 0, v19
	v_fmac_f32_e32 v168, v51, v18
	v_max_f32_e32 v18, 0, v20
	v_fmac_f32_e32 v168, v52, v18
	v_max_f32_e32 v18, 0, v21
	v_fmac_f32_e32 v168, v53, v18
	v_max_f32_e32 v18, 0, v22
	v_fma_f32 v18, v54, v18, 0
	v_max_f32_e32 v19, 0, v23
	v_fmac_f32_e32 v18, v55, v19
	v_max_f32_e32 v19, 0, v24
	v_fmac_f32_e32 v18, v56, v19
	v_max_f32_e32 v19, 0, v25
	v_fmac_f32_e32 v18, v57, v19
	v_max_f32_e32 v19, 0, v26
	v_fma_f32 v20, v58, v19, 0
	v_max_f32_e32 v19, 0, v27
	v_fmac_f32_e32 v20, v59, v19
	v_max_f32_e32 v19, 0, v28
	v_fmac_f32_e32 v20, v60, v19
	v_max_f32_e32 v19, 0, v29
	v_fmac_f32_e32 v20, v61, v19
	v_max_f32_e32 v19, 0, v30
	v_fma_f32 v19, v62, v19, 0
	v_max_f32_e32 v21, 0, v31
	v_fmac_f32_e32 v19, v63, v21
	v_max_f32_e32 v21, 0, v32
	v_fmac_f32_e32 v19, v64, v21
	v_max_f32_e32 v21, 0, v33
	v_fmac_f32_e32 v19, v65, v21
	s_mov_b64 s[30:31], -1
	s_and_b64 vcc, exec, s[28:29]
	s_cbranch_vccz .LBB0_2653
	v_permlane32_swap_b32_e32 v168, v20
	v_add_f32_e32 v25, v168, v20
	v_ashrrev_i32_e32 v26, 31, v25
	v_bitop3_b32 v25, v26, v25, s82 bitop3:0x36
	v_lshrrev_b32_e32 v26, 22, v25
	s_nop 0
	v_permlane32_swap_b32_e32 v18, v19
	v_cmp_le_i32_e32 vcc, v26, v101
	s_and_saveexec_b64 s[28:29], vcc
	s_xor_b64 s[28:29], exec, s[28:29]
	s_cbranch_execz .LBB0_2644
	v_sub_u32_e32 v26, v26, v100
	v_cmp_lt_i32_e32 vcc, -1, v26
	s_and_saveexec_b64 s[30:31], vcc
	s_cbranch_execz .LBB0_2643
	v_lshrrev_b32_e32 v25, v113, v25
	v_and_b32_e32 v25, v25, v114
	v_lshl_or_b32 v25, v26, v111, v25
	v_lshlrev_b32_e32 v26, 1, v25
	v_and_b32_e32 v26, -4, v26
	v_lshlrev_b32_e32 v25, 4, v25
	v_add_u32_e32 v26, v123, v26
	v_lshlrev_b32_e64 v25, v25, 1
	ds_add_u32 v26, v25

; DI void phase_index(const Params& p, unsigned char* lds) {
;     ...
;                 } else if (PASS == 3) {
;                     if (valid) {
;                         const int k10 = (int)(uk >> 22), d = k10 - b1v[qq];
;                         if (k10 > hiv[qq]) cntA[qq] += 1;
;                         else if (d >= 0) {
;                             const unsigned bin = ((unsigned)d << sbv[qq]) | ((uk >> (22 - sbv[qq])) & ((1u << sbv[qq]) - 1u));
;                             const unsigned a = bin << 1;
;                             atomicAdd((unsigned*)(lds + hbase0 + qq * 2048 + (a & ~3u)), 1u << ((a & 2u) << 3));
;                         }
;                     }
.LBB0_2644:
	s_or_saveexec_b64 s[28:29], s[28:29]
	v_mov_b32_e32 v165, v167
	s_xor_b64 exec, exec, s[28:29]
	v_add_u32_e32 v165, 1, v167
	s_or_b64 exec, exec, s[28:29]
	v_add_f32_e32 v21, v18, v19
	v_ashrrev_i32_e32 v22, 31, v21
	v_bitop3_b32 v21, v22, v21, s82 bitop3:0x36
	v_lshrrev_b32_e32 v22, 22, v21
	v_cmp_le_i32_e32 vcc, v22, v103
	s_and_saveexec_b64 s[28:29], vcc
	s_xor_b64 s[28:29], exec, s[28:29]
	s_cbranch_execz .LBB0_2650
	v_sub_u32_e32 v22, v22, v102
	v_cmp_lt_i32_e32 vcc, -1, v22
	s_and_saveexec_b64 s[30:31], vcc
	s_cbranch_execz .LBB0_2649
	v_lshrrev_b32_e32 v21, v115, v21
	v_and_b32_e32 v21, v21, v116
	v_lshl_or_b32 v21, v22, v112, v21
	v_lshlrev_b32_e32 v22, 1, v21
	v_and_b32_e32 v22, -4, v22
	v_lshlrev_b32_e32 v21, 4, v21
	v_add_u32_e32 v22, v123, v22
	v_lshlrev_b32_e64 v21, v21, 1
	ds_add_u32 v22, v21 offset:2048

; DI void phase_index(const Params& p, unsigned char* lds) {
;     ...
;             for (int q = 0; q < 4; ++q) {
;                 float pr = 0.f;
; #pragma unroll
;                 for (int e = 0; e < 4; ++e) pr += wq[q][e] * fmaxf(s[4 * q + e], 0.f);
;                 tot[q] = xhalf_sum(pr);
;             }
;             const int key = k0 + 32 * kb + r32;
; #pragma unroll
;             for (int qq = 0; qq < 2; ++qq) {
;                 const float t_lo = tot[qq], t_hi = tot[2 + qq];
;                 const float sc = ((lane & 32) ? t_hi : t_lo) + 0.0f;
;                 const unsigned ub = __float_as_uint(sc);
;                 const unsigned uk = ub ^ ((unsigned)((int)ub >> 31) | 0x80000000u);
;                 const bool valid = DIAG ? (key <= tq0 + qq) : true;
;                 if (PASS == 0) {
;                     if (valid) { const unsigned a = (uk >> 21) & 0x7feu; atomicAdd((unsigned*)(lds + hbase0 + qq * 2048 + (a & ~3u)), 1u << ((a & 2u) << 3)); }
;                 } else if (PASS == 1) {
;                     if (valid && (int)(uk >> 22) == b1v[qq]) { const unsigned a = (uk >> 11) & 0x7feu; atomicAdd((unsigned*)(lds + hbase0 + qq * 2048 + (a & ~3u)), 1u << ((a & 2u) << 3)); }
;                 } else if (PASS == 3) {
;                     if (valid) {
;                         const int k10 = (int)(uk >> 22), d = k10 - b1v[qq];
;                         if (k10 > hiv[qq]) cntA[qq] += 1;
;                         else if (d >= 0) {
;                             const unsigned bin = ((unsigned)d << sbv[qq]) | ((uk >> (22 - sbv[qq])) & ((1u << sbv[qq]) - 1u));
;                             const unsigned a = bin << 1;
;                             atomicAdd((unsigned*)(lds + hbase0 + qq * 2048 + (a & ~3u)), 1u << ((a & 2u) << 3));
;                         }
;                     }
;                 } else {
;                     const int k20 = (int)(uk >> kshv[qq]);
;                     const u64 bg = __ballot(valid && k20 > tauv[qq]);
;                     const u64 be = __ballot(valid && k20 == tauv[qq]);
;                     Gm[qq] |= (bg & 0xffffffffull) << (32 * kb); Gm[2 + qq] |= (bg >> 32) << (32 * kb);
;                     Em[qq] |= (be & 0xffffffffull) << (32 * kb); Em[2 + qq] |= (be >> 32) << (32 * kb);
;                 }
.LBB0_3524:
	v_max_f32_e32 v18, 0, v18
	v_fma_f32 v18, v50, v18, 0
	v_max_f32_e32 v19, 0, v19
	v_fmac_f32_e32 v18, v51, v19
	v_max_f32_e32 v19, 0, v20
	v_fmac_f32_e32 v18, v52, v19
	v_max_f32_e32 v19, 0, v21
	v_fmac_f32_e32 v18, v53, v19
	v_max_f32_e32 v19, 0, v22
	v_fma_f32 v19, v54, v19, 0
	v_max_f32_e32 v20, 0, v23
	v_fmac_f32_e32 v19, v55, v20
	v_max_f32_e32 v20, 0, v24
	v_fmac_f32_e32 v19, v56, v20
	v_max_f32_e32 v20, 0, v25
	v_fmac_f32_e32 v19, v57, v20
	v_max_f32_e32 v20, 0, v26
	v_fma_f32 v20, v58, v20, 0
	v_max_f32_e32 v21, 0, v27
	v_fmac_f32_e32 v20, v59, v21
	v_max_f32_e32 v21, 0, v28
	v_fmac_f32_e32 v20, v60, v21
	v_max_f32_e32 v21, 0, v29
	v_fmac_f32_e32 v20, v61, v21
	v_max_f32_e32 v21, 0, v30
	v_fma_f32 v21, v62, v21, 0
	v_max_f32_e32 v22, 0, v31
	v_fmac_f32_e32 v21, v63, v22
	v_max_f32_e32 v22, 0, v32
	v_fmac_f32_e32 v21, v64, v22
	v_max_f32_e32 v22, 0, v33
	v_fmac_f32_e32 v21, v65, v22
	s_mov_b64 s[28:29], -1
	s_and_b64 vcc, exec, s[58:59]
	s_cbranch_vccz .LBB0_3526
	v_permlane32_swap_b32_e32 v18, v20
	v_permlane32_swap_b32_e32 v19, v21
	v_pk_add_f32 v[22:23], v[18:19], v[20:21]
	s_mov_b64 s[28:29], 0
	s_nop 0
	v_ashrrev_i32_e32 v24, 31, v23
	v_ashrrev_i32_e32 v25, 31, v22
	v_or_b32_e32 v24, 0x80000000, v24
	v_or_b32_e32 v25, 0x80000000, v25
	v_xor_b32_e32 v23, v24, v23
	v_xor_b32_e32 v22, v25, v22
	v_lshrrev_b32_e32 v23, v83, v23
	v_lshrrev_b32_e32 v22, v106, v22
	v_cmp_gt_i32_e64 s[58:59], v22, v100
	v_cmp_eq_u32_e64 s[68:69], v22, v100
	v_cmp_gt_i32_e64 s[30:31], v23, v1
	v_cmp_eq_u32_e64 s[26:27], v23, v1

; DI void phase_index(const Params& p, unsigned char* lds) {
;     ...
;             for (int q = 0; q < 4; ++q) {
;                 float pr = 0.f;
; #pragma unroll
;                 for (int e = 0; e < 4; ++e) pr += wq[q][e] * fmaxf(s[4 * q + e], 0.f);
;                 tot[q] = xhalf_sum(pr);
;             }
;             const int key = k0 + 32 * kb + r32;
; #pragma unroll
;             for (int qq = 0; qq < 2; ++qq) {
;                 const float t_lo = tot[qq], t_hi = tot[2 + qq];
;                 const float sc = ((lane & 32) ? t_hi : t_lo) + 0.0f;
;                 const unsigned ub = __float_as_uint(sc);
;                 const unsigned uk = ub ^ ((unsigned)((int)ub >> 31) | 0x80000000u);
;                 const bool valid = DIAG ? (key <= tq0 + qq) : true;
;                 if (PASS == 0) {
;                     if (valid) { const unsigned a = (uk >> 21) & 0x7feu; atomicAdd((unsigned*)(lds + hbase0 + qq * 2048 + (a & ~3u)), 1u << ((a & 2u) << 3)); }
;                 } else if (PASS == 1) {
;                     if (valid && (int)(uk >> 22) == b1v[qq]) { const unsigned a = (uk >> 11) & 0x7feu; atomicAdd((unsigned*)(lds + hbase0 + qq * 2048 + (a & ~3u)), 1u << ((a & 2u) << 3)); }
;                 } else if (PASS == 3) {
;                     if (valid) {
;                         const int k10 = (int)(uk >> 22), d = k10 - b1v[qq];
;                         if (k10 > hiv[qq]) cntA[qq] += 1;
;                         else if (d >= 0) {
;                             const unsigned bin = ((unsigned)d << sbv[qq]) | ((uk >> (22 - sbv[qq])) & ((1u << sbv[qq]) - 1u));
;                             const unsigned a = bin << 1;
;                             atomicAdd((unsigned*)(lds + hbase0 + qq * 2048 + (a & ~3u)), 1u << ((a & 2u) << 3));
;                         }
;                     }
;                 } else {
;                     const int k20 = (int)(uk >> kshv[qq]);
;                     const u64 bg = __ballot(valid && k20 > tauv[qq]);
;                     const u64 be = __ballot(valid && k20 == tauv[qq]);
;                     Gm[qq] |= (bg & 0xffffffffull) << (32 * kb); Gm[2 + qq] |= (bg >> 32) << (32 * kb);
;                     Em[qq] |= (be & 0xffffffffull) << (32 * kb); Em[2 + qq] |= (be >> 32) << (32 * kb);
;                 }
.LBB0_3555:
	v_permlane32_swap_b32_e32 v114, v116
	v_permlane32_swap_b32_e32 v115, v117
	v_pk_add_f32 v[164:165], v[114:115], v[116:117]
	s_nop 0
	s_nop 0
	v_ashrrev_i32_e32 v166, 31, v165
	v_ashrrev_i32_e32 v167, 31, v164
	v_or_b32_e32 v166, 0x80000000, v166
	v_or_b32_e32 v167, 0x80000000, v167
	v_xor_b32_e32 v165, v166, v165
	v_xor_b32_e32 v164, v167, v164
	v_lshrrev_b32_e32 v165, v83, v165
	v_lshrrev_b32_e32 v164, v106, v164
	v_cmp_gt_i32_e64 s[52:53], v164, v100
	v_cmp_eq_u32_e64 s[56:57], v164, v100
	v_cmp_gt_i32_e64 s[50:51], v165, v1
	v_cmp_eq_u32_e64 s[54:55], v165, v1
	s_lshl_b32 s28, s36, 6
	v_or_b32_e32 v164, s28, v194
	s_cbranch_execnz .LBB0_3522
